# silu(cvec) table build de-serialised (ten loads in flight, then exp/div/LDS writes) in phase 0 and in the phase-2 hook copy
# speedup vs baseline: 1.0115x; 1.0115x over previous
.LBB0_1094:
	s_movk_i32 s0, 0x1400
	v_cmp_gt_i32_e32 vcc, s0, v192
	s_and_saveexec_b64 s[0:1], vcc
	v_readlane_b32 s44, v254, 34
	s_movk_i32 s26, 0x3ff
	v_readlane_b32 s45, v254, 35
	s_cbranch_execz .LBB0_1101
	v_lshlrev_b32_e32 v9, 2, v192
	v_lshl_add_u32 v2, v192, 2, 0
	global_load_dword v10, v9, s[14:15]
	global_load_dword v11, v9, s[14:15] offset:2048
	global_load_dword v12, v9, s[12:13]
	global_load_dword v13, v9, s[12:13] offset:2048
	s_add_u32 s22, s12, 0x1000
	s_addc_u32 s23, s13, 0
	global_load_dword v14, v9, s[22:23]
	global_load_dword v15, v9, s[22:23] offset:2048
	s_add_u32 s22, s12, 0x2000
	s_addc_u32 s23, s13, 0
	global_load_dword v16, v9, s[22:23]
	global_load_dword v17, v9, s[22:23] offset:2048
	s_add_u32 s22, s12, 0x3000
	s_addc_u32 s23, s13, 0
	global_load_dword v18, v9, s[22:23]
	global_load_dword v19, v9, s[22:23] offset:2048
	s_waitcnt vmcnt(9)
	v_mov_b32_e32 v0, v10
	v_mul_f32_e32 v1, 0xbfb8aa3b, v0
	v_exp_f32_e32 v1, v1
	s_nop 0
	v_add_f32_e32 v1, 1.0, v1
	v_div_scale_f32 v3, s[20:21], v1, v1, v0
	v_rcp_f32_e32 v5, v3
	v_div_scale_f32 v6, vcc, v0, v1, v0
	v_fma_f32 v7, -v3, v5, 1.0
	v_fmac_f32_e32 v5, v7, v5
	v_mul_f32_e32 v7, v6, v5
	v_fma_f32 v8, -v3, v7, v6
	v_fmac_f32_e32 v7, v8, v5
	v_fma_f32 v3, -v3, v7, v6
	v_div_fmas_f32 v3, v3, v5, v7
	v_div_fixup_f32 v0, v3, v1, v0
	ds_write_b32 v2, v0
	s_waitcnt vmcnt(8)
	v_mov_b32_e32 v0, v11
	v_mul_f32_e32 v1, 0xbfb8aa3b, v0
	v_exp_f32_e32 v1, v1
	s_nop 0
	v_add_f32_e32 v1, 1.0, v1
	v_div_scale_f32 v3, s[20:21], v1, v1, v0
	v_rcp_f32_e32 v5, v3
	v_div_scale_f32 v6, vcc, v0, v1, v0
	v_fma_f32 v7, -v3, v5, 1.0
	v_fmac_f32_e32 v5, v7, v5
	v_mul_f32_e32 v7, v6, v5
	v_fma_f32 v8, -v3, v7, v6
	v_fmac_f32_e32 v7, v8, v5
	v_fma_f32 v3, -v3, v7, v6
	v_div_fmas_f32 v3, v3, v5, v7
	v_div_fixup_f32 v0, v3, v1, v0
	ds_write_b32 v2, v0 offset:2048
	s_waitcnt vmcnt(7)
	v_mov_b32_e32 v0, v12
	v_mul_f32_e32 v1, 0xbfb8aa3b, v0
	v_exp_f32_e32 v1, v1
	s_nop 0
	v_add_f32_e32 v1, 1.0, v1
	v_div_scale_f32 v3, s[20:21], v1, v1, v0
	v_rcp_f32_e32 v5, v3
	v_div_scale_f32 v6, vcc, v0, v1, v0
	v_fma_f32 v7, -v3, v5, 1.0
	v_fmac_f32_e32 v5, v7, v5
	v_mul_f32_e32 v7, v6, v5
	v_fma_f32 v8, -v3, v7, v6
	v_fmac_f32_e32 v7, v8, v5
	v_fma_f32 v3, -v3, v7, v6
	v_div_fmas_f32 v3, v3, v5, v7
	v_div_fixup_f32 v0, v3, v1, v0
	ds_write_b32 v2, v0 offset:4096
	s_waitcnt vmcnt(6)
	v_mov_b32_e32 v0, v13
	v_mul_f32_e32 v1, 0xbfb8aa3b, v0
	v_exp_f32_e32 v1, v1
	s_nop 0
	v_add_f32_e32 v1, 1.0, v1
	v_div_scale_f32 v3, s[20:21], v1, v1, v0
	v_rcp_f32_e32 v5, v3
	v_div_scale_f32 v6, vcc, v0, v1, v0
	v_fma_f32 v7, -v3, v5, 1.0
	v_fmac_f32_e32 v5, v7, v5
	v_mul_f32_e32 v7, v6, v5
	v_fma_f32 v8, -v3, v7, v6
	v_fmac_f32_e32 v7, v8, v5
	v_fma_f32 v3, -v3, v7, v6
	v_div_fmas_f32 v3, v3, v5, v7
	v_div_fixup_f32 v0, v3, v1, v0
	ds_write_b32 v2, v0 offset:6144
	s_waitcnt vmcnt(5)
	v_mov_b32_e32 v0, v14
	v_mul_f32_e32 v1, 0xbfb8aa3b, v0
	v_exp_f32_e32 v1, v1
	s_nop 0
	v_add_f32_e32 v1, 1.0, v1
	v_div_scale_f32 v3, s[20:21], v1, v1, v0
	v_rcp_f32_e32 v5, v3
	v_div_scale_f32 v6, vcc, v0, v1, v0
	v_fma_f32 v7, -v3, v5, 1.0
	v_fmac_f32_e32 v5, v7, v5
	v_mul_f32_e32 v7, v6, v5
	v_fma_f32 v8, -v3, v7, v6
	v_fmac_f32_e32 v7, v8, v5
	v_fma_f32 v3, -v3, v7, v6
	v_div_fmas_f32 v3, v3, v5, v7
	v_div_fixup_f32 v0, v3, v1, v0
	ds_write_b32 v2, v0 offset:8192
	s_waitcnt vmcnt(4)
	v_mov_b32_e32 v0, v15
	v_mul_f32_e32 v1, 0xbfb8aa3b, v0
	v_exp_f32_e32 v1, v1
	s_nop 0
	v_add_f32_e32 v1, 1.0, v1
	v_div_scale_f32 v3, s[20:21], v1, v1, v0
	v_rcp_f32_e32 v5, v3
	v_div_scale_f32 v6, vcc, v0, v1, v0
	v_fma_f32 v7, -v3, v5, 1.0
	v_fmac_f32_e32 v5, v7, v5
	v_mul_f32_e32 v7, v6, v5
	v_fma_f32 v8, -v3, v7, v6
	v_fmac_f32_e32 v7, v8, v5
	v_fma_f32 v3, -v3, v7, v6
	v_div_fmas_f32 v3, v3, v5, v7
	v_div_fixup_f32 v0, v3, v1, v0
	ds_write_b32 v2, v0 offset:10240
	s_waitcnt vmcnt(3)
	v_mov_b32_e32 v0, v16
	v_mul_f32_e32 v1, 0xbfb8aa3b, v0
	v_exp_f32_e32 v1, v1
	s_nop 0
	v_add_f32_e32 v1, 1.0, v1
	v_div_scale_f32 v3, s[20:21], v1, v1, v0
	v_rcp_f32_e32 v5, v3
	v_div_scale_f32 v6, vcc, v0, v1, v0
	v_fma_f32 v7, -v3, v5, 1.0
	v_fmac_f32_e32 v5, v7, v5
	v_mul_f32_e32 v7, v6, v5
	v_fma_f32 v8, -v3, v7, v6
	v_fmac_f32_e32 v7, v8, v5
	v_fma_f32 v3, -v3, v7, v6
	v_div_fmas_f32 v3, v3, v5, v7
	v_div_fixup_f32 v0, v3, v1, v0
	ds_write_b32 v2, v0 offset:12288
	s_waitcnt vmcnt(2)
	v_mov_b32_e32 v0, v17
	v_mul_f32_e32 v1, 0xbfb8aa3b, v0
	v_exp_f32_e32 v1, v1
	s_nop 0
	v_add_f32_e32 v1, 1.0, v1
	v_div_scale_f32 v3, s[20:21], v1, v1, v0
	v_rcp_f32_e32 v5, v3
	v_div_scale_f32 v6, vcc, v0, v1, v0
	v_fma_f32 v7, -v3, v5, 1.0
	v_fmac_f32_e32 v5, v7, v5
	v_mul_f32_e32 v7, v6, v5
	v_fma_f32 v8, -v3, v7, v6
	v_fmac_f32_e32 v7, v8, v5
	v_fma_f32 v3, -v3, v7, v6
	v_div_fmas_f32 v3, v3, v5, v7
	v_div_fixup_f32 v0, v3, v1, v0
	ds_write_b32 v2, v0 offset:14336
	s_waitcnt vmcnt(1)
	v_mov_b32_e32 v0, v18
	v_mul_f32_e32 v1, 0xbfb8aa3b, v0
	v_exp_f32_e32 v1, v1
	s_nop 0
	v_add_f32_e32 v1, 1.0, v1
	v_div_scale_f32 v3, s[20:21], v1, v1, v0
	v_rcp_f32_e32 v5, v3
	v_div_scale_f32 v6, vcc, v0, v1, v0
	v_fma_f32 v7, -v3, v5, 1.0
	v_fmac_f32_e32 v5, v7, v5
	v_mul_f32_e32 v7, v6, v5
	v_fma_f32 v8, -v3, v7, v6
	v_fmac_f32_e32 v7, v8, v5
	v_fma_f32 v3, -v3, v7, v6
	v_div_fmas_f32 v3, v3, v5, v7
	v_div_fixup_f32 v0, v3, v1, v0
	ds_write_b32 v2, v0 offset:16384
	s_waitcnt vmcnt(0)
	v_mov_b32_e32 v0, v19
	v_mul_f32_e32 v1, 0xbfb8aa3b, v0
	v_exp_f32_e32 v1, v1
	s_nop 0
	v_add_f32_e32 v1, 1.0, v1
	v_div_scale_f32 v3, s[20:21], v1, v1, v0
	v_rcp_f32_e32 v5, v3
	v_div_scale_f32 v6, vcc, v0, v1, v0
	v_fma_f32 v7, -v3, v5, 1.0
	v_fmac_f32_e32 v5, v7, v5
	v_mul_f32_e32 v7, v6, v5
	v_fma_f32 v8, -v3, v7, v6
	v_fmac_f32_e32 v7, v8, v5
	v_fma_f32 v3, -v3, v7, v6
	v_div_fmas_f32 v3, v3, v5, v7
	v_div_fixup_f32 v0, v3, v1, v0
	ds_write_b32 v2, v0 offset:18432

.Ltq_exit:
	s_waitcnt vmcnt(0) lgkmcnt(0)
	s_mov_b64 s[84:85], s[60:61]
	v_readlane_b32 s0, v255, 24
	v_readlane_b32 s1, v255, 25
	v_readlane_b32 s2, v255, 26
	v_readlane_b32 s3, v255, 27
	v_readlane_b32 s20, v255, 28
	v_readlane_b32 s21, v255, 29
	v_readlane_b32 s22, v255, 30
	v_readlane_b32 s23, v255, 31
	v_readlane_b32 s26, v255, 32
	v_readlane_b32 s33, v255, 33
	v_readlane_b32 s34, v255, 34
	v_readlane_b32 s35, v255, 35
	v_readlane_b32 s36, v255, 36
	v_readlane_b32 s37, v255, 37
	v_readlane_b32 s38, v255, 38
	v_readlane_b32 s39, v255, 39
	v_readlane_b32 s40, v255, 40
	v_readlane_b32 s41, v255, 41
	v_readlane_b32 s42, v255, 42
	v_readlane_b32 s43, v255, 43
	v_readlane_b32 s56, v255, 44
	v_readlane_b32 s57, v255, 45
	v_readlane_b32 s58, v255, 46
	v_readlane_b32 s60, v255, 47
	v_readlane_b32 s61, v255, 48
	v_readlane_b32 s80, v255, 49
	v_readlane_b32 s81, v255, 50
	v_readlane_b32 s82, v255, 51
	v_readlane_b32 s83, v255, 52
	v_readlane_b32 s86, v255, 53
	v_readlane_b32 s87, v255, 54
	v_readlane_b32 s88, v255, 55
	v_readlane_b32 s89, v255, 56
	v_readlane_b32 s90, v255, 57
	v_readlane_b32 s91, v255, 58
	v_readlane_b32 s92, v255, 59
	v_readlane_b32 s93, v255, 60
	v_readlane_b32 s94, v255, 61
	v_readlane_b32 s95, v255, 62
	s_nop 4
	s_barrier
	v_writelane_b32 v255, s0, 24
	v_writelane_b32 v255, s1, 25
	v_writelane_b32 v255, s2, 26
	v_writelane_b32 v255, s3, 27
	v_writelane_b32 v255, s20, 28
	v_writelane_b32 v255, s21, 29
	v_writelane_b32 v255, s22, 30
	v_writelane_b32 v255, s23, 31
	v_writelane_b32 v255, s26, 32
	v_writelane_b32 v255, s34, 33
	v_writelane_b32 v255, s35, 34
	v_writelane_b32 v255, s36, 35
	v_writelane_b32 v255, s37, 36
	v_writelane_b32 v255, s38, 37
	v_writelane_b32 v255, s39, 38
	v_writelane_b32 v255, s40, 39
	v_writelane_b32 v255, s41, 40
	v_writelane_b32 v255, s44, 41
	v_writelane_b32 v255, s45, 42
	v_writelane_b32 v255, s56, 43
	v_readlane_b32 s56, v255, 6
	s_nop 3
	s_movk_i32 s0, 0x1400
	v_cmp_gt_i32_e32 vcc, s0, v192
	s_and_saveexec_b64 s[0:1], vcc
	v_readlane_b32 s44, v254, 34
	s_movk_i32 s26, 0x3ff
	v_readlane_b32 s45, v254, 35
	s_cbranch_execz .Lal_1101
	v_lshlrev_b32_e32 v9, 2, v192
	v_lshl_add_u32 v2, v192, 2, 0
	global_load_dword v10, v9, s[14:15]
	global_load_dword v11, v9, s[14:15] offset:2048
	global_load_dword v12, v9, s[12:13]
	global_load_dword v13, v9, s[12:13] offset:2048
	s_add_u32 s22, s12, 0x1000
	s_addc_u32 s23, s13, 0
	global_load_dword v14, v9, s[22:23]
	global_load_dword v15, v9, s[22:23] offset:2048
	s_add_u32 s22, s12, 0x2000
	s_addc_u32 s23, s13, 0
	global_load_dword v16, v9, s[22:23]
	global_load_dword v17, v9, s[22:23] offset:2048
	s_add_u32 s22, s12, 0x3000
	s_addc_u32 s23, s13, 0
	global_load_dword v18, v9, s[22:23]
	global_load_dword v19, v9, s[22:23] offset:2048
	s_waitcnt vmcnt(9)
	v_mov_b32_e32 v0, v10
	v_mul_f32_e32 v1, 0xbfb8aa3b, v0
	v_exp_f32_e32 v1, v1
	s_nop 0
	v_add_f32_e32 v1, 1.0, v1
	v_div_scale_f32 v3, s[20:21], v1, v1, v0
	v_rcp_f32_e32 v5, v3
	v_div_scale_f32 v6, vcc, v0, v1, v0
	v_fma_f32 v7, -v3, v5, 1.0
	v_fmac_f32_e32 v5, v7, v5
	v_mul_f32_e32 v7, v6, v5
	v_fma_f32 v8, -v3, v7, v6
	v_fmac_f32_e32 v7, v8, v5
	v_fma_f32 v3, -v3, v7, v6
	v_div_fmas_f32 v3, v3, v5, v7
	v_div_fixup_f32 v0, v3, v1, v0
	ds_write_b32 v2, v0
	s_waitcnt vmcnt(8)
	v_mov_b32_e32 v0, v11
	v_mul_f32_e32 v1, 0xbfb8aa3b, v0
	v_exp_f32_e32 v1, v1
	s_nop 0
	v_add_f32_e32 v1, 1.0, v1
	v_div_scale_f32 v3, s[20:21], v1, v1, v0
	v_rcp_f32_e32 v5, v3
	v_div_scale_f32 v6, vcc, v0, v1, v0
	v_fma_f32 v7, -v3, v5, 1.0
	v_fmac_f32_e32 v5, v7, v5
	v_mul_f32_e32 v7, v6, v5
	v_fma_f32 v8, -v3, v7, v6
	v_fmac_f32_e32 v7, v8, v5
	v_fma_f32 v3, -v3, v7, v6
	v_div_fmas_f32 v3, v3, v5, v7
	v_div_fixup_f32 v0, v3, v1, v0
	ds_write_b32 v2, v0 offset:2048
	s_waitcnt vmcnt(7)
	v_mov_b32_e32 v0, v12
	v_mul_f32_e32 v1, 0xbfb8aa3b, v0
	v_exp_f32_e32 v1, v1
	s_nop 0
	v_add_f32_e32 v1, 1.0, v1
	v_div_scale_f32 v3, s[20:21], v1, v1, v0
	v_rcp_f32_e32 v5, v3
	v_div_scale_f32 v6, vcc, v0, v1, v0
	v_fma_f32 v7, -v3, v5, 1.0
	v_fmac_f32_e32 v5, v7, v5
	v_mul_f32_e32 v7, v6, v5
	v_fma_f32 v8, -v3, v7, v6
	v_fmac_f32_e32 v7, v8, v5
	v_fma_f32 v3, -v3, v7, v6
	v_div_fmas_f32 v3, v3, v5, v7
	v_div_fixup_f32 v0, v3, v1, v0
	ds_write_b32 v2, v0 offset:4096
	s_waitcnt vmcnt(6)
	v_mov_b32_e32 v0, v13
	v_mul_f32_e32 v1, 0xbfb8aa3b, v0
	v_exp_f32_e32 v1, v1
	s_nop 0
	v_add_f32_e32 v1, 1.0, v1
	v_div_scale_f32 v3, s[20:21], v1, v1, v0
	v_rcp_f32_e32 v5, v3
	v_div_scale_f32 v6, vcc, v0, v1, v0
	v_fma_f32 v7, -v3, v5, 1.0
	v_fmac_f32_e32 v5, v7, v5
	v_mul_f32_e32 v7, v6, v5
	v_fma_f32 v8, -v3, v7, v6
	v_fmac_f32_e32 v7, v8, v5
	v_fma_f32 v3, -v3, v7, v6
	v_div_fmas_f32 v3, v3, v5, v7
	v_div_fixup_f32 v0, v3, v1, v0
	ds_write_b32 v2, v0 offset:6144
	s_waitcnt vmcnt(5)
	v_mov_b32_e32 v0, v14
	v_mul_f32_e32 v1, 0xbfb8aa3b, v0
	v_exp_f32_e32 v1, v1
	s_nop 0
	v_add_f32_e32 v1, 1.0, v1
	v_div_scale_f32 v3, s[20:21], v1, v1, v0
	v_rcp_f32_e32 v5, v3
	v_div_scale_f32 v6, vcc, v0, v1, v0
	v_fma_f32 v7, -v3, v5, 1.0
	v_fmac_f32_e32 v5, v7, v5
	v_mul_f32_e32 v7, v6, v5
	v_fma_f32 v8, -v3, v7, v6
	v_fmac_f32_e32 v7, v8, v5
	v_fma_f32 v3, -v3, v7, v6
	v_div_fmas_f32 v3, v3, v5, v7
	v_div_fixup_f32 v0, v3, v1, v0
	ds_write_b32 v2, v0 offset:8192
	s_waitcnt vmcnt(4)
	v_mov_b32_e32 v0, v15
	v_mul_f32_e32 v1, 0xbfb8aa3b, v0
	v_exp_f32_e32 v1, v1
	s_nop 0
	v_add_f32_e32 v1, 1.0, v1
	v_div_scale_f32 v3, s[20:21], v1, v1, v0
	v_rcp_f32_e32 v5, v3
	v_div_scale_f32 v6, vcc, v0, v1, v0
	v_fma_f32 v7, -v3, v5, 1.0
	v_fmac_f32_e32 v5, v7, v5
	v_mul_f32_e32 v7, v6, v5
	v_fma_f32 v8, -v3, v7, v6
	v_fmac_f32_e32 v7, v8, v5
	v_fma_f32 v3, -v3, v7, v6
	v_div_fmas_f32 v3, v3, v5, v7
	v_div_fixup_f32 v0, v3, v1, v0
	ds_write_b32 v2, v0 offset:10240
	s_waitcnt vmcnt(3)
	v_mov_b32_e32 v0, v16
	v_mul_f32_e32 v1, 0xbfb8aa3b, v0
	v_exp_f32_e32 v1, v1
	s_nop 0
	v_add_f32_e32 v1, 1.0, v1
	v_div_scale_f32 v3, s[20:21], v1, v1, v0
	v_rcp_f32_e32 v5, v3
	v_div_scale_f32 v6, vcc, v0, v1, v0
	v_fma_f32 v7, -v3, v5, 1.0
	v_fmac_f32_e32 v5, v7, v5
	v_mul_f32_e32 v7, v6, v5
	v_fma_f32 v8, -v3, v7, v6
	v_fmac_f32_e32 v7, v8, v5
	v_fma_f32 v3, -v3, v7, v6
	v_div_fmas_f32 v3, v3, v5, v7
	v_div_fixup_f32 v0, v3, v1, v0
	ds_write_b32 v2, v0 offset:12288
	s_waitcnt vmcnt(2)
	v_mov_b32_e32 v0, v17
	v_mul_f32_e32 v1, 0xbfb8aa3b, v0
	v_exp_f32_e32 v1, v1
	s_nop 0
	v_add_f32_e32 v1, 1.0, v1
	v_div_scale_f32 v3, s[20:21], v1, v1, v0
	v_rcp_f32_e32 v5, v3
	v_div_scale_f32 v6, vcc, v0, v1, v0
	v_fma_f32 v7, -v3, v5, 1.0
	v_fmac_f32_e32 v5, v7, v5
	v_mul_f32_e32 v7, v6, v5
	v_fma_f32 v8, -v3, v7, v6
	v_fmac_f32_e32 v7, v8, v5
	v_fma_f32 v3, -v3, v7, v6
	v_div_fmas_f32 v3, v3, v5, v7
	v_div_fixup_f32 v0, v3, v1, v0
	ds_write_b32 v2, v0 offset:14336
	s_waitcnt vmcnt(1)
	v_mov_b32_e32 v0, v18
	v_mul_f32_e32 v1, 0xbfb8aa3b, v0
	v_exp_f32_e32 v1, v1
	s_nop 0
	v_add_f32_e32 v1, 1.0, v1
	v_div_scale_f32 v3, s[20:21], v1, v1, v0
	v_rcp_f32_e32 v5, v3
	v_div_scale_f32 v6, vcc, v0, v1, v0
	v_fma_f32 v7, -v3, v5, 1.0
	v_fmac_f32_e32 v5, v7, v5
	v_mul_f32_e32 v7, v6, v5
	v_fma_f32 v8, -v3, v7, v6
	v_fmac_f32_e32 v7, v8, v5
	v_fma_f32 v3, -v3, v7, v6
	v_div_fmas_f32 v3, v3, v5, v7
	v_div_fixup_f32 v0, v3, v1, v0
	ds_write_b32 v2, v0 offset:16384
	s_waitcnt vmcnt(0)
	v_mov_b32_e32 v0, v19
	v_mul_f32_e32 v1, 0xbfb8aa3b, v0
	v_exp_f32_e32 v1, v1
	s_nop 0
	v_add_f32_e32 v1, 1.0, v1
	v_div_scale_f32 v3, s[20:21], v1, v1, v0
	v_rcp_f32_e32 v5, v3
	v_div_scale_f32 v6, vcc, v0, v1, v0
	v_fma_f32 v7, -v3, v5, 1.0
	v_fmac_f32_e32 v5, v7, v5
	v_mul_f32_e32 v7, v6, v5
	v_fma_f32 v8, -v3, v7, v6
	v_fmac_f32_e32 v7, v8, v5
	v_fma_f32 v3, -v3, v7, v6
	v_div_fmas_f32 v3, v3, v5, v7
	v_div_fixup_f32 v0, v3, v1, v0
	ds_write_b32 v2, v0 offset:18432
